# v5 + nt cache hint on the rw2 loader LDS-DMA record loads (streaming, no reuse)
# speedup vs baseline: 1.0070x; 1.0064x over previous
; #define GAS __attribute__((address_space(1)))
; __device__ __forceinline__ void rw2_phase(const Ctx& c0) { const Ctx c = fresh(c0);
;     ...
;         const GAS char* gsrc = (j == 0) ? (const GAS char*)(ws + WS_AF) + (size_t)h * 128 * 8192 : (j == 1) ? (const GAS char*)(ws + WS_BF) + (size_t)h * 128 * 8192 : (j == 2) ? (const GAS char*)(ws + WS_VK2F) + (size_t)h * 128 * 8192 : (const GAS char*)(ws + WS_PL) + (size_t)h * 128 * 1024;
;         gsrc += lane * 16;
;     ...
;         RW2_ISSUE(0); RW2_ISSUE(1); RW2_ISSUE(2); RW2_ISSUE(3);
.LBB0_2436:
	s_ashr_i32 s1, s0, 31
	s_add_u32 s7, s2, s8
	s_addc_u32 s12, s3, s9
	s_lshl_b64 s[10:11], s[0:1], s6
	s_add_u32 s0, s7, s10
	s_addc_u32 s1, s12, s11
	v_ashrrev_i32_e32 v83, 31, v82
	v_lshl_add_u64 v[2:3], s[0:1], 0, v[82:83]
	s_mov_b64 s[12:13], 0x400
	v_lshl_add_u64 v[8:9], v[2:3], 0, s[12:13]
	s_mov_b64 s[12:13], 0x800
	s_cmp_lg_u32 s5, 3
	v_lshl_add_u64 v[6:7], v[2:3], 0, s[12:13]
	s_mov_b64 s[12:13], 0xc00
	s_mov_b64 s[0:1], -1
	s_cselect_b64 s[6:7], -1, 0
	s_cmp_eq_u32 s5, 3
	v_lshl_add_u64 v[4:5], v[2:3], 0, s[12:13]
	s_cbranch_scc1 .LBB0_2438
	s_lshl_b32 s12, s5, 13
	s_or_b32 m0, s12, 0x400
	s_mov_b64 s[0:1], 0x1000
	global_load_lds_dwordx4 v[2:3], off nt
	s_or_b32 m0, s12, 0x800
	v_lshl_add_u64 v[10:11], v[2:3], 0, s[0:1]
	global_load_lds_dwordx4 v[8:9], off nt
	s_or_b32 m0, s12, 0xc00
	s_mov_b64 s[0:1], 0x1400
	global_load_lds_dwordx4 v[6:7], off nt
	s_or_b32 m0, s12, 0x1000
	s_nop 0
	global_load_lds_dwordx4 v[4:5], off nt
	s_or_b32 m0, s12, 0x1400
	s_nop 0
	global_load_lds_dwordx4 v[10:11], off nt
	v_lshl_add_u64 v[10:11], v[2:3], 0, s[0:1]
	s_or_b32 m0, s12, 0x1800
	s_mov_b64 s[0:1], 0x1800
	global_load_lds_dwordx4 v[10:11], off nt
	v_lshl_add_u64 v[10:11], v[2:3], 0, s[0:1]
	s_or_b32 m0, s12, 0x1c00
	s_mov_b64 s[0:1], 0x1c00
	global_load_lds_dwordx4 v[10:11], off nt
	v_lshl_add_u64 v[10:11], v[2:3], 0, s[0:1]
	s_add_i32 m0, s12, 0x2000
	s_mov_b64 s[0:1], 0
	global_load_lds_dwordx4 v[10:11], off nt
.LBB0_2438:
	s_andn2_b64 vcc, exec, s[0:1]
	s_cbranch_vccnz .LBB0_2440
	s_movk_i32 m0, 0x6400
	s_nop 0
	global_load_lds_dwordx4 v[2:3], off nt
.LBB0_2440:
	v_cndmask_b32_e64 v0, 0, 1, s[6:7]
	v_cmp_ne_u32_e64 s[0:1], 1, v0
	s_andn2_b64 vcc, exec, s[6:7]
	s_mov_b64 s[12:13], -1
	s_cbranch_vccnz .LBB0_2448
	s_mov_b64 s[12:13], 0x2000
	s_lshl_b32 s14, s5, 13
	v_lshl_add_u64 v[10:11], v[2:3], 0, s[12:13]
	s_add_i32 m0, s14, 0x6800
	s_mov_b64 s[12:13], 0x2400
	global_load_lds_dwordx4 v[10:11], off nt
	v_lshl_add_u64 v[10:11], v[2:3], 0, s[12:13]
	s_add_i32 m0, s14, 0x6c00
	s_mov_b64 s[12:13], 0x2800
	global_load_lds_dwordx4 v[10:11], off nt
	v_lshl_add_u64 v[10:11], v[2:3], 0, s[12:13]
	s_add_i32 m0, s14, 0x7000
	s_mov_b64 s[12:13], 0x2c00
	global_load_lds_dwordx4 v[10:11], off nt
	v_lshl_add_u64 v[10:11], v[2:3], 0, s[12:13]
	s_add_i32 m0, s14, 0x7400
	s_mov_b64 s[12:13], 0x3000
	global_load_lds_dwordx4 v[10:11], off nt
	v_lshl_add_u64 v[10:11], v[2:3], 0, s[12:13]
	s_add_i32 m0, s14, 0x7800
	s_mov_b64 s[12:13], 0x3400
	global_load_lds_dwordx4 v[10:11], off nt
	v_lshl_add_u64 v[10:11], v[2:3], 0, s[12:13]
	s_add_i32 m0, s14, 0x7c00
	s_mov_b64 s[12:13], 0x3800
	global_load_lds_dwordx4 v[10:11], off nt
	v_lshl_add_u64 v[10:11], v[2:3], 0, s[12:13]
	s_or_b32 m0, s14, 0x8000
	s_mov_b64 s[12:13], 0x3c00
	global_load_lds_dwordx4 v[10:11], off nt
	v_lshl_add_u64 v[10:11], v[2:3], 0, s[12:13]
	s_or_b32 m0, s14, 0x8400
	s_nop 0
	global_load_lds_dwordx4 v[10:11], off nt
	s_cbranch_execz .LBB0_2449

; __device__ __forceinline__ void rw2_phase(const Ctx& c0) { const Ctx c = fresh(c0);
;     ...
;         RW2_ISSUE(0); RW2_ISSUE(1); RW2_ISSUE(2); RW2_ISSUE(3);
.LBB0_2443:
	s_mov_b64 s[12:13], 0x4000
	s_lshl_b32 s14, s5, 13
	v_lshl_add_u64 v[8:9], v[2:3], 0, s[12:13]
	s_add_i32 m0, s14, 0xcc00
	s_mov_b64 s[12:13], 0x4400
	global_load_lds_dwordx4 v[8:9], off nt
	v_lshl_add_u64 v[8:9], v[2:3], 0, s[12:13]
	s_add_i32 m0, s14, 0xd000
	s_mov_b64 s[12:13], 0x4800
	global_load_lds_dwordx4 v[8:9], off nt
	v_lshl_add_u64 v[8:9], v[2:3], 0, s[12:13]
	s_add_i32 m0, s14, 0xd400
	s_mov_b64 s[12:13], 0x4c00
	global_load_lds_dwordx4 v[8:9], off nt
	v_lshl_add_u64 v[8:9], v[2:3], 0, s[12:13]
	s_add_i32 m0, s14, 0xd800
	s_mov_b64 s[12:13], 0x5000
	global_load_lds_dwordx4 v[8:9], off nt
	v_lshl_add_u64 v[8:9], v[2:3], 0, s[12:13]
	s_add_i32 m0, s14, 0xdc00
	s_mov_b64 s[12:13], 0x5400
	global_load_lds_dwordx4 v[8:9], off nt
	v_lshl_add_u64 v[8:9], v[2:3], 0, s[12:13]
	s_add_i32 m0, s14, 0xe000
	s_mov_b64 s[12:13], 0x5800
	global_load_lds_dwordx4 v[8:9], off nt
	v_lshl_add_u64 v[8:9], v[2:3], 0, s[12:13]
	s_add_i32 m0, s14, 0xe400
	s_mov_b64 s[12:13], 0x5c00
	global_load_lds_dwordx4 v[8:9], off nt
	v_lshl_add_u64 v[8:9], v[2:3], 0, s[12:13]
	s_add_i32 m0, s14, 0xe800
	s_nop 0
	global_load_lds_dwordx4 v[8:9], off nt
	s_cbranch_execz .LBB0_2451

; __device__ __forceinline__ void rw2_phase(const Ctx& c0) { const Ctx c = fresh(c0);
;     ...
;         RW2_ISSUE(0); RW2_ISSUE(1); RW2_ISSUE(2); RW2_ISSUE(3);
.LBB0_2445:
	s_mov_b64 s[12:13], 0x6000
	s_lshl_b32 s14, s5, 13
	v_lshl_add_u64 v[6:7], v[2:3], 0, s[12:13]
	s_add_i32 m0, s14, 0x13000
	s_mov_b64 s[12:13], 0x6400
	global_load_lds_dwordx4 v[6:7], off nt
	v_lshl_add_u64 v[6:7], v[2:3], 0, s[12:13]
	s_add_i32 m0, s14, 0x13400
	s_mov_b64 s[12:13], 0x6800
	global_load_lds_dwordx4 v[6:7], off nt
	v_lshl_add_u64 v[6:7], v[2:3], 0, s[12:13]
	s_add_i32 m0, s14, 0x13800
	s_mov_b64 s[12:13], 0x6c00
	global_load_lds_dwordx4 v[6:7], off nt
	v_lshl_add_u64 v[6:7], v[2:3], 0, s[12:13]
	s_add_i32 m0, s14, 0x13c00
	s_mov_b64 s[12:13], 0x7000
	global_load_lds_dwordx4 v[6:7], off nt
	v_lshl_add_u64 v[6:7], v[2:3], 0, s[12:13]
	s_add_i32 m0, s14, 0x14000
	s_mov_b64 s[12:13], 0x7400
	global_load_lds_dwordx4 v[6:7], off nt
	v_lshl_add_u64 v[6:7], v[2:3], 0, s[12:13]
	s_add_i32 m0, s14, 0x14400
	s_mov_b64 s[12:13], 0x7800
	global_load_lds_dwordx4 v[6:7], off nt
	v_lshl_add_u64 v[6:7], v[2:3], 0, s[12:13]
	s_add_i32 m0, s14, 0x14800
	s_mov_b64 s[12:13], 0x7c00
	global_load_lds_dwordx4 v[6:7], off nt
	v_lshl_add_u64 v[6:7], v[2:3], 0, s[12:13]
	s_add_i32 m0, s14, 0x14c00
	s_nop 0
	global_load_lds_dwordx4 v[6:7], off nt
	s_cbranch_execz .LBB0_2453

; __device__ __forceinline__ void rw2_phase(const Ctx& c0) { const Ctx c = fresh(c0);
;     ...
;         RW2_ISSUE(0); RW2_ISSUE(1); RW2_ISSUE(2); RW2_ISSUE(3);
.LBB0_2449:
	s_mov_b32 m0, 0xc800
	s_nop 0
	global_load_lds_dwordx4 v[8:9], off nt
	s_and_b64 vcc, exec, s[0:1]
	s_mov_b64 s[12:13], -1
	s_cbranch_vccz .LBB0_2443

; __device__ __forceinline__ void rw2_phase(const Ctx& c0) { const Ctx c = fresh(c0);
;     ...
;         RW2_ISSUE(0); RW2_ISSUE(1); RW2_ISSUE(2); RW2_ISSUE(3);
.LBB0_2451:
	s_mov_b32 m0, 0x12c00
	s_nop 0
	global_load_lds_dwordx4 v[6:7], off nt
	s_and_b64 vcc, exec, s[0:1]
	s_mov_b64 s[12:13], -1
	s_cbranch_vccz .LBB0_2445

; __device__ __forceinline__ void rw2_phase(const Ctx& c0) { const Ctx c = fresh(c0);
;     ...
;         RW2_ISSUE(0); RW2_ISSUE(1); RW2_ISSUE(2); RW2_ISSUE(3);
.LBB0_2453:
	s_mov_b32 m0, 0x19000
	s_nop 0
	global_load_lds_dwordx4 v[4:5], off nt
	s_mov_b64 s[12:13], -1
	s_and_b64 vcc, exec, s[6:7]
	s_cbranch_vccnz .LBB0_2447

; #define RW2_WAIT(k8, k1) do { if (j == 3) asm volatile("s_waitcnt vmcnt(" #k1 ")" ::: "memory"); else asm volatile("s_waitcnt vmcnt(" #k8 ")" ::: "memory"); } while (0)
; __device__ __forceinline__ void rw2_phase(const Ctx& c0) { const Ctx c = fresh(c0);
;     ...
;         for (int n = 0; n < 128; ++n) {
;             if (n + 4 < 128) { RW2_ISSUE(n + 4); RW2_WAIT(24, 3); }
.LBB0_2478:
	s_andn2_b64 vcc, exec, s[8:9]
	s_cbranch_vccnz .LBB0_2457
	s_add_i32 s8, s10, 4
	s_mul_i32 s9, s8, 0xcd
	s_bfe_u32 s9, s9, 0x6000a
	s_mul_i32 s9, s9, 5
	s_sub_i32 s8, s8, s9
	s_and_b32 s11, s8, 0xff
	s_mulk_i32 s11, 0x6400
	s_and_b64 vcc, exec, s[0:1]
	s_mov_b64 s[8:9], -1
	s_cbranch_vccnz .LBB0_2483
	v_lshl_add_u64 v[6:7], v[2:3], 0, s[2:3]
	s_mov_b64 s[8:9], 0x8000
	s_add_i32 s12, s11, s5
	v_lshl_add_u64 v[8:9], v[6:7], 0, s[8:9]
	s_add_i32 m0, s12, 0x400
	s_mov_b64 s[8:9], 0x8400
	global_load_lds_dwordx4 v[8:9], off nt
	v_lshl_add_u64 v[8:9], v[6:7], 0, s[8:9]
	s_add_i32 m0, s12, 0x800
	s_mov_b64 s[8:9], 0x8800
	global_load_lds_dwordx4 v[8:9], off nt
	v_lshl_add_u64 v[8:9], v[6:7], 0, s[8:9]
	s_add_i32 m0, s12, 0xc00
	s_mov_b64 s[8:9], 0x8c00
	global_load_lds_dwordx4 v[8:9], off nt
	v_lshl_add_u64 v[8:9], v[6:7], 0, s[8:9]
	s_add_i32 m0, s12, 0x1000
	s_mov_b64 s[8:9], 0x9000
	global_load_lds_dwordx4 v[8:9], off nt
	v_lshl_add_u64 v[8:9], v[6:7], 0, s[8:9]
	s_add_i32 m0, s12, 0x1400
	s_mov_b64 s[8:9], 0x9400
	global_load_lds_dwordx4 v[8:9], off nt
	v_lshl_add_u64 v[8:9], v[6:7], 0, s[8:9]
	s_add_i32 m0, s12, 0x1800
	s_mov_b64 s[8:9], 0x9800
	global_load_lds_dwordx4 v[8:9], off nt
	v_lshl_add_u64 v[8:9], v[6:7], 0, s[8:9]
	s_add_i32 m0, s12, 0x1c00
	s_mov_b64 s[8:9], 0x9c00
	global_load_lds_dwordx4 v[8:9], off nt
	v_lshl_add_u64 v[6:7], v[6:7], 0, s[8:9]
	s_add_i32 m0, s12, 0x2000
	s_nop 0
	global_load_lds_dwordx4 v[6:7], off nt
	s_cbranch_execz .LBB0_2484

; #define RW2_BAR() do { __builtin_amdgcn_s_barrier(); asm volatile("" ::: "memory"); } while (0)
; #define RW2_WAIT(k8, k1) do { if (j == 3) asm volatile("s_waitcnt vmcnt(" #k1 ")" ::: "memory"); else asm volatile("s_waitcnt vmcnt(" #k8 ")" ::: "memory"); } while (0)
; __device__ __forceinline__ void rw2_phase(const Ctx& c0) { const Ctx c = fresh(c0);
;     ...
;         RW2_ISSUE(0); RW2_ISSUE(1); RW2_ISSUE(2); RW2_ISSUE(3);
;         RW2_WAIT(24, 3);
;         RW2_BAR();
;         for (int n = 0; n < 128; ++n) {
;             if (n + 4 < 128) { RW2_ISSUE(n + 4); RW2_WAIT(24, 3); }
.LBB0_2484:
	s_add_i32 m0, s11, 0x6400
	s_nop 0
	global_load_lds_dwordx4 v[4:5], off nt
	s_mov_b64 s[8:9], -1
	s_and_b64 vcc, exec, s[6:7]
	s_cbranch_vccnz .LBB0_2482
